# stack + decode loop loads in saddr+voffset form (20 v_lshl_add_u64 address adds per iteration removed)
# baseline (speedup 1.0000x reference)
.LBB0_883:
	s_and_b64 vcc, exec, s[0:1]
	s_cbranch_vccz .LBB0_885
	s_load_dword s0, s[34:35], 0x0
	s_waitcnt lgkmcnt(0)
	s_ashr_i32 s1, s0, 31
	s_lshl_b64 s[0:1], s[0:1], 7
	s_or_b64 s[0:1], s[0:1], s[54:55]
	s_lshl_b64 s[64:65], s[0:1], 10
	s_add_u32 s64, s42, s64
	s_addc_u32 s65, s43, s65
	global_load_dwordx4 v[120:123], v160, s[64:65] nt
	global_load_dwordx4 v[152:155], v162, s[64:65] nt
	global_load_dwordx4 v[148:151], v164, s[64:65] nt
	global_load_dwordx4 v[144:147], v166, s[64:65] nt
	global_load_dwordx4 v[140:143], v168, s[64:65] nt
	global_load_dwordx4 v[136:139], v170, s[64:65] nt
	global_load_dwordx4 v[132:135], v172, s[64:65] nt
	s_nop 0
	global_load_dwordx4 v[128:131], v174, s[64:65] nt
	s_lshl_b64 s[0:1], s[0:1], 8
	v_readlane_b32 s64, v255, 26
	v_readlane_b32 s65, v255, 27
	s_add_u32 s0, s64, s0
	s_addc_u32 s1, s65, s1
	global_load_dwordx4 v[84:87], v176, s[0:1] nt
	s_nop 0
	global_load_dwordx4 v[124:127], v178, s[0:1] nt
	v_readlane_b32 s66, v255, 28
	v_readlane_b32 s67, v255, 29
	s_branch .LBB0_886

.LBB0_896:
	s_and_b64 vcc, exec, s[0:1]
	s_cbranch_vccz .LBB0_898
	s_load_dword s0, s[26:27], 0x0
	s_and_b32 s64, s50, 64
	s_waitcnt lgkmcnt(0)
	s_ashr_i32 s1, s0, 31
	s_lshl_b64 s[0:1], s[0:1], 7
	s_or_b32 s0, s0, s64
	s_lshl_b64 s[64:65], s[0:1], 10
	s_add_u32 s64, s42, s64
	s_addc_u32 s65, s43, s65
	global_load_dwordx4 v[80:83], v160, s[64:65] nt
	global_load_dwordx4 v[88:91], v162, s[64:65] nt
	global_load_dwordx4 v[92:95], v164, s[64:65] nt
	s_nop 0
	global_load_dwordx4 v[96:99], v166, s[64:65] nt
	s_nop 0
	global_load_dwordx4 v[100:103], v168, s[64:65] nt
	s_nop 0
	global_load_dwordx4 v[108:111], v170, s[64:65] nt
	global_load_dwordx4 v[112:115], v172, s[64:65] nt
	s_nop 0
	global_load_dwordx4 v[116:119], v174, s[64:65] nt
	s_lshl_b64 s[0:1], s[0:1], 8
	v_readlane_b32 s64, v255, 26
	v_readlane_b32 s65, v255, 27
	s_add_u32 s0, s64, s0
	s_addc_u32 s1, s65, s1
	global_load_dwordx4 v[76:79], v176, s[0:1] nt
	s_nop 0
	global_load_dwordx4 v[104:107], v178, s[0:1] nt
	v_readlane_b32 s66, v255, 28
	v_readlane_b32 s67, v255, 29
	s_branch .LBB0_899
